# dilated attention: masked fast paths also for diagonal (kt=4) and far (kt=0) tiles (one compare + cndmask per element instead of generic 11-instr mask/bias)
# baseline (speedup 1.0000x reference)
; __device__ __forceinline__ void dil_unit(const bf16_t* QKV, float* scr, bf16_t* O, int b, int h, int blk, char* shm) {
;     ...
;             const int k = wid + 8 * rep, res = k & (d - 1), c = k >> lg, tq0 = T0 + res + d * 32 * c;
;             const int tq = tq0 + d * r32;
;             bf16x8 qf[4];
; #pragma unroll
;             for (int s = 0; s < 4; ++s) qf[s] = *(const bf16x8*)(Qh + (rb + tq) * 1536 + s * 16 + hi * 8);
;             f32x16 o[2]; o[0] = f32x16{}; o[1] = f32x16{};
;             float mrun = -1e30f, lrun = 0.f;
.LBB0_1247:
	s_add_i32 s0, s0, s28
	s_bfm_b32 s1, s30, 0
	s_and_b32 s1, s0, s1
	s_ashr_i32 s0, s0, s30
	s_add_i32 s8, s1, s93
	s_lshl_b32 s0, s0, s34
	s_add_i32 s8, s8, s0
	v_add_u32_e32 v174, s8, v180
	v_ashrrev_i32_e32 v175, 31, v174
	v_lshl_add_u64 v[172:173], v[174:175], 0, s[18:19]
	v_mad_u64_u32 v[0:1], s[0:1], v172, s81, v[160:161]
	v_mad_i32_i24 v1, v173, s81, v1
	s_mov_b32 s0, 4
	global_load_dwordx4 v[48:51], v[0:1], off
	global_load_dwordx4 v[52:55], v[0:1], off offset:32
	global_load_dwordx4 v[56:59], v[0:1], off offset:64
	global_load_dwordx4 v[60:63], v[0:1], off offset:96
	s_lshl_b32 s0, s0, 5
	s_add_i32 s3, s0, 0xffffff80
	v_or_b32_e32 v0, s3, v167
	v_lshlrev_b32_e32 v0, s30, v0
	v_add_u32_e32 v0, s8, v0
	v_max_i32_e32 v0, 0, v0
	v_add_u32_e32 v0, s18, v0
	v_mad_u64_u32 v[4:5], s[0:1], v0, s81, v[162:163]
	v_or_b32_e32 v28, s3, v176
	global_load_dwordx4 v[0:3], v[4:5], off
	global_load_dwordx4 v[24:27], v[4:5], off offset:32
	global_load_dwordx4 v[20:23], v[4:5], off offset:64
	global_load_dwordx4 v[16:19], v[4:5], off offset:96
	v_lshlrev_b32_e32 v4, s30, v28
	v_or_b32_e32 v8, 8, v28
	v_add_u32_e32 v4, s8, v4
	v_lshlrev_b32_e32 v8, s30, v8
	v_or_b32_e32 v12, 16, v28
	v_max_i32_e32 v4, 0, v4
	v_add_u32_e32 v8, s8, v8
	v_lshlrev_b32_e32 v12, s30, v12
	v_or_b32_e32 v28, 24, v28
	v_add_u32_e32 v4, s18, v4
	v_max_i32_e32 v8, 0, v8
	v_add_u32_e32 v12, s8, v12
	v_lshlrev_b32_e32 v28, s30, v28
	v_mad_u64_u32 v[4:5], s[0:1], v4, s81, v[164:165]
	v_add_u32_e32 v8, s18, v8
	v_max_i32_e32 v12, 0, v12
	v_add_u32_e32 v28, s8, v28
	global_load_dwordx4 v[4:7], v[4:5], off
	v_mad_u64_u32 v[8:9], s[0:1], v8, s81, v[164:165]
	v_add_u32_e32 v12, s18, v12
	v_max_i32_e32 v28, 0, v28
	global_load_dwordx4 v[8:11], v[8:9], off
	v_mad_u64_u32 v[12:13], s[0:1], v12, s81, v[164:165]
	v_add_u32_e32 v28, s18, v28
	global_load_dwordx4 v[12:15], v[12:13], off
	v_mad_u64_u32 v[28:29], s[0:1], v28, s81, v[164:165]
	global_load_dwordx4 v[28:31], v[28:29], off
	s_mov_b32 s0, 3
	s_lshl_b32 s0, s0, 5
	s_add_i32 s3, s0, 0xffffff80
	v_or_b32_e32 v32, s3, v167
	v_lshlrev_b32_e32 v32, s30, v32
	v_add_u32_e32 v32, s8, v32
	v_max_i32_e32 v32, 0, v32
	v_add_u32_e32 v32, s18, v32
	v_mad_u64_u32 v[36:37], s[0:1], v32, s81, v[162:163]
	s_waitcnt vmcnt(16)
	v_or_b32_e32 v64, s3, v176
	global_load_dwordx4 v[32:35], v[36:37], off
	global_load_dwordx4 v[132:135], v[36:37], off offset:32
	global_load_dwordx4 v[128:131], v[36:37], off offset:64
	global_load_dwordx4 v[124:127], v[36:37], off offset:96
	v_lshlrev_b32_e32 v36, s30, v64
	v_or_b32_e32 v40, 8, v64
	v_or_b32_e32 v44, 16, v64
	v_or_b32_e32 v64, 24, v64
	v_lshlrev_b32_e32 v40, s30, v40
	v_lshlrev_b32_e32 v44, s30, v44
	v_lshlrev_b32_e32 v64, s30, v64
	v_add_u32_e32 v36, s8, v36
	v_add_u32_e32 v40, s8, v40
	v_add_u32_e32 v44, s8, v44
	v_add_u32_e32 v64, s8, v64
	v_max_i32_e32 v36, 0, v36
	v_max_i32_e32 v40, 0, v40
	v_max_i32_e32 v44, 0, v44
	v_max_i32_e32 v64, 0, v64
	v_add_u32_e32 v36, s18, v36
	v_add_u32_e32 v40, s18, v40
	v_add_u32_e32 v44, s18, v44
	v_add_u32_e32 v64, s18, v64
	v_mad_u64_u32 v[36:37], s[0:1], v36, s81, v[164:165]
	v_mad_u64_u32 v[40:41], s[0:1], v40, s81, v[164:165]
	v_mad_u64_u32 v[44:45], s[0:1], v44, s81, v[164:165]
	v_mad_u64_u32 v[64:65], s[0:1], v64, s81, v[164:165]
	s_mov_b32 s0, 2
	global_load_dwordx4 v[36:39], v[36:37], off
	s_nop 0
	global_load_dwordx4 v[40:43], v[40:41], off
	s_nop 0
	global_load_dwordx4 v[44:47], v[44:45], off
	s_nop 0
	global_load_dwordx4 v[136:139], v[64:65], off
	s_lshl_b32 s0, s0, 5
	s_add_i32 s3, s0, 0xffffff80
	v_or_b32_e32 v64, s3, v167
	v_or_b32_e32 v78, s3, v176
	v_lshlrev_b32_e32 v64, s30, v64
	v_lshlrev_b32_e32 v76, s30, v78
	v_add_u32_e32 v64, s8, v64
	v_add_u32_e32 v76, s8, v76
	v_max_i32_e32 v64, 0, v64
	v_max_i32_e32 v76, 0, v76
	v_add_u32_e32 v64, s18, v64
	v_add_u32_e32 v76, s18, v76
	v_mad_u64_u32 v[64:65], s[0:1], v64, s81, v[162:163]
	v_mad_u64_u32 v[76:77], s[0:1], v76, s81, v[164:165]
	global_load_dwordx4 v[92:95], v[64:65], off
	global_load_dwordx4 v[72:75], v[64:65], off offset:32
	global_load_dwordx4 v[68:71], v[64:65], off offset:64
	s_nop 0
	global_load_dwordx4 v[64:67], v[64:65], off offset:96
	s_not_b32 s3, s8
	global_load_dwordx4 v[112:115], v[76:77], off
	v_or_b32_e32 v76, 8, v78
	v_lshlrev_b32_e32 v76, s30, v76
	v_add_u32_e32 v76, s8, v76
	v_max_i32_e32 v76, 0, v76
	v_add_u32_e32 v76, s18, v76
	v_mad_u64_u32 v[76:77], s[0:1], v76, s81, v[164:165]
	global_load_dwordx4 v[116:119], v[76:77], off
	v_or_b32_e32 v76, 16, v78
	v_lshlrev_b32_e32 v76, s30, v76
	v_add_u32_e32 v76, s8, v76
	v_max_i32_e32 v76, 0, v76
	v_add_u32_e32 v76, s18, v76
	v_mad_u64_u32 v[76:77], s[0:1], v76, s81, v[164:165]
	global_load_dwordx4 v[120:123], v[76:77], off
	v_or_b32_e32 v76, 24, v78
	v_lshlrev_b32_e32 v76, s30, v76
	v_add_u32_e32 v76, s8, v76
	v_max_i32_e32 v76, 0, v76
	v_add_u32_e32 v76, s18, v76
	v_mad_u64_u32 v[76:77], s[0:1], v76, s81, v[164:165]
	s_mov_b32 s0, 4
	global_load_dwordx4 v[140:143], v[76:77], off
	s_waitcnt lgkmcnt(0)
	s_waitcnt vmcnt(19)
	ds_write_b128 v178, v[4:7]
	s_waitcnt vmcnt(18)
	ds_write_b128 v178, v[8:11] offset:512
	s_waitcnt vmcnt(17)
	ds_write_b128 v178, v[12:15] offset:1024
	s_waitcnt vmcnt(16)
	ds_write_b128 v178, v[28:31] offset:1536
	v_mfma_f32_32x32x16_bf16 v[0:15], v[0:3], v[48:51], 0
	v_mfma_f32_32x32x16_bf16 v[0:15], v[24:27], v[52:55], v[0:15]
	v_mfma_f32_32x32x16_bf16 v[0:15], v[20:23], v[56:59], v[0:15]
	v_mfma_f32_32x32x16_bf16 v[0:15], v[16:19], v[60:63], v[0:15]
	v_lshl_add_u32 v16, s0, 5, v177
	v_sub_u32_e32 v211, v167, v16
	v_cmp_lt_i32_e32 vcc, 0x80, v211
	v_lshlrev_b32_e32 v170, s30, v16
	s_nop 2
	s_cbranch_vccnz .Ldil_slow_0
	v_cmp_ge_i32_e32 vcc, s3, v170
	s_nop 3
	s_cbranch_vccnz .Ldil_slow_0
	v_cvt_f32_i32_e32 v170, v211
	v_mul_f32_e32 v170, v171, v170
	v_fma_f32 v0, v0, v210, -v170
	v_cmp_le_i32_e32 vcc, 0, v211
	v_fma_f32 v1, v1, v210, -v170
	v_fmamk_f32 v1, v171, 0x3f800000, v1
	v_cndmask_b32_e32 v0, v243, v0, vcc
	v_cmp_le_i32_e32 vcc, 1, v211
	v_fma_f32 v17, v2, v210, -v170
	v_fmamk_f32 v17, v171, 0x40000000, v17
	v_cndmask_b32_e32 v1, v243, v1, vcc
	v_cmp_le_i32_e32 vcc, 2, v211
	v_fma_f32 v19, v3, v210, -v170
	v_fmamk_f32 v19, v171, 0x40400000, v19
	v_cndmask_b32_e32 v17, v243, v17, vcc
	v_cmp_le_i32_e32 vcc, 3, v211
	v_fma_f32 v4, v4, v210, -v170
	v_fmamk_f32 v4, v171, 0x41000000, v4
	v_cndmask_b32_e32 v19, v243, v19, vcc
	v_cmp_le_i32_e32 vcc, 8, v211
	v_fma_f32 v5, v5, v210, -v170
	v_fmamk_f32 v5, v171, 0x41100000, v5
	v_cndmask_b32_e32 v4, v243, v4, vcc
	v_cmp_le_i32_e32 vcc, 9, v211
	v_fma_f32 v6, v6, v210, -v170
	v_fmamk_f32 v6, v171, 0x41200000, v6
	v_cndmask_b32_e32 v5, v243, v5, vcc
	v_cmp_le_i32_e32 vcc, 10, v211
	v_fma_f32 v7, v7, v210, -v170
	v_fmamk_f32 v7, v171, 0x41300000, v7
	v_cndmask_b32_e32 v6, v243, v6, vcc
	v_cmp_le_i32_e32 vcc, 11, v211
	v_fma_f32 v8, v8, v210, -v170
	v_fmamk_f32 v8, v171, 0x41800000, v8
	v_cndmask_b32_e32 v7, v243, v7, vcc
	v_cmp_le_i32_e32 vcc, 16, v211
	v_fma_f32 v9, v9, v210, -v170
	v_fmamk_f32 v9, v171, 0x41880000, v9
	v_cndmask_b32_e32 v8, v243, v8, vcc
	v_cmp_le_i32_e32 vcc, 17, v211
	v_fma_f32 v10, v10, v210, -v170
	v_fmamk_f32 v10, v171, 0x41900000, v10
	v_cndmask_b32_e32 v9, v243, v9, vcc
	v_cmp_le_i32_e32 vcc, 18, v211
	v_fma_f32 v11, v11, v210, -v170
	v_fmamk_f32 v11, v171, 0x41980000, v11
	v_cndmask_b32_e32 v10, v243, v10, vcc
	v_cmp_le_i32_e32 vcc, 19, v211
	v_fma_f32 v12, v12, v210, -v170
	v_fmamk_f32 v12, v171, 0x41c00000, v12
	v_cndmask_b32_e32 v11, v243, v11, vcc
	v_cmp_le_i32_e32 vcc, 24, v211
	v_fma_f32 v13, v13, v210, -v170
	v_fmamk_f32 v13, v171, 0x41c80000, v13
	v_cndmask_b32_e32 v12, v243, v12, vcc
	v_cmp_le_i32_e32 vcc, 25, v211
	v_fma_f32 v14, v14, v210, -v170
	v_fmamk_f32 v14, v171, 0x41d00000, v14
	v_cndmask_b32_e32 v13, v243, v13, vcc
	v_cmp_le_i32_e32 vcc, 26, v211
	v_fma_f32 v2, v15, v210, -v170
	v_fmamk_f32 v2, v171, 0x41d80000, v2
	v_cndmask_b32_e32 v14, v243, v14, vcc
	v_cmp_le_i32_e32 vcc, 27, v211
	s_nop 1
	v_cndmask_b32_e32 v2, v243, v2, vcc
	s_branch .Ldil_join_0
.Ldil_slow_0:
	v_sub_u32_e32 v17, v167, v16
	v_cvt_f32_i32_e32 v211, v17
	v_lshlrev_b32_e32 v18, s30, v16
	v_cmp_gt_u32_e32 vcc, s6, v17
	v_cmp_lt_i32_e64 s[0:1], s3, v18
	v_or_b32_e32 v17, 1, v16
	s_nop 4
	v_mov_b32_e32 v170, v0
	v_pk_mul_f32 v[18:19], v[170:171], v[210:211]
	s_and_b64 vcc, vcc, s[0:1]
	v_sub_f32_e32 v0, v18, v19
	v_sub_u32_e32 v18, v167, v17
	v_cvt_f32_i32_e32 v211, v18
	v_lshlrev_b32_e32 v17, s30, v17
	v_mov_b32_e32 v170, v1
	v_cndmask_b32_e32 v0, v243, v0, vcc
	v_cmp_gt_u32_e32 vcc, s6, v18
	v_cmp_lt_i32_e64 s[0:1], s3, v17
	v_pk_mul_f32 v[18:19], v[170:171], v[210:211]
	v_or_b32_e32 v17, 2, v16
	v_sub_f32_e32 v1, v18, v19
	v_sub_u32_e32 v18, v167, v17
	v_cvt_f32_i32_e32 v211, v18
	s_and_b64 vcc, vcc, s[0:1]
	v_lshlrev_b32_e32 v17, s30, v17
	v_mov_b32_e32 v170, v2
	v_cndmask_b32_e32 v1, v243, v1, vcc
	v_cmp_gt_u32_e32 vcc, s6, v18
	v_cmp_lt_i32_e64 s[0:1], s3, v17
	v_pk_mul_f32 v[18:19], v[170:171], v[210:211]
	s_and_b64 vcc, vcc, s[0:1]
	v_sub_f32_e32 v2, v18, v19
	v_cndmask_b32_e32 v17, v243, v2, vcc
	v_or_b32_e32 v2, 3, v16
	v_sub_u32_e32 v18, v167, v2
	v_cvt_f32_i32_e32 v211, v18
	v_lshlrev_b32_e32 v2, s30, v2
	v_mov_b32_e32 v170, v3
	v_cmp_gt_u32_e32 vcc, s6, v18
	v_cmp_lt_i32_e64 s[0:1], s3, v2
	v_pk_mul_f32 v[2:3], v[170:171], v[210:211]
	s_and_b64 vcc, vcc, s[0:1]
	v_sub_f32_e32 v2, v2, v3
	v_cndmask_b32_e32 v19, v243, v2, vcc
	v_or_b32_e32 v2, 8, v16
	v_sub_u32_e32 v3, v167, v2
	v_cvt_f32_i32_e32 v211, v3
	v_lshlrev_b32_e32 v2, s30, v2
	v_mov_b32_e32 v170, v4
	v_cmp_gt_u32_e32 vcc, s6, v3
	v_cmp_lt_i32_e64 s[0:1], s3, v2
	v_pk_mul_f32 v[2:3], v[170:171], v[210:211]
	s_and_b64 vcc, vcc, s[0:1]
	v_sub_f32_e32 v2, v2, v3
	v_cndmask_b32_e32 v4, v243, v2, vcc
	v_or_b32_e32 v2, 9, v16
	v_sub_u32_e32 v3, v167, v2
	v_cvt_f32_i32_e32 v211, v3
	v_lshlrev_b32_e32 v2, s30, v2
	v_mov_b32_e32 v170, v5
	v_cmp_gt_u32_e32 vcc, s6, v3
	v_cmp_lt_i32_e64 s[0:1], s3, v2
	v_pk_mul_f32 v[2:3], v[170:171], v[210:211]
	s_and_b64 vcc, vcc, s[0:1]
	v_sub_f32_e32 v2, v2, v3
	v_cndmask_b32_e32 v5, v243, v2, vcc
	v_or_b32_e32 v2, 10, v16
	v_sub_u32_e32 v3, v167, v2
	v_cvt_f32_i32_e32 v211, v3
	v_lshlrev_b32_e32 v2, s30, v2
	v_mov_b32_e32 v170, v6
	v_cmp_gt_u32_e32 vcc, s6, v3
	v_cmp_lt_i32_e64 s[0:1], s3, v2
	v_pk_mul_f32 v[2:3], v[170:171], v[210:211]
	s_and_b64 vcc, vcc, s[0:1]
	v_sub_f32_e32 v2, v2, v3
	v_cndmask_b32_e32 v6, v243, v2, vcc
	v_or_b32_e32 v2, 11, v16
	v_sub_u32_e32 v3, v167, v2
	v_cvt_f32_i32_e32 v211, v3
	v_lshlrev_b32_e32 v2, s30, v2
	v_mov_b32_e32 v170, v7
	v_cmp_gt_u32_e32 vcc, s6, v3
	v_cmp_lt_i32_e64 s[0:1], s3, v2
	v_pk_mul_f32 v[2:3], v[170:171], v[210:211]
	s_and_b64 vcc, vcc, s[0:1]
	v_sub_f32_e32 v2, v2, v3
	v_cndmask_b32_e32 v7, v243, v2, vcc
	v_or_b32_e32 v2, 16, v16
	v_sub_u32_e32 v3, v167, v2
	v_cvt_f32_i32_e32 v211, v3
	v_lshlrev_b32_e32 v2, s30, v2
	v_mov_b32_e32 v170, v8
	v_cmp_gt_u32_e32 vcc, s6, v3
	v_cmp_lt_i32_e64 s[0:1], s3, v2
	v_pk_mul_f32 v[2:3], v[170:171], v[210:211]
	s_and_b64 vcc, vcc, s[0:1]
	v_sub_f32_e32 v2, v2, v3
	v_cndmask_b32_e32 v8, v243, v2, vcc
	v_or_b32_e32 v2, 17, v16
	v_sub_u32_e32 v3, v167, v2
	v_cvt_f32_i32_e32 v211, v3
	v_lshlrev_b32_e32 v2, s30, v2
	v_mov_b32_e32 v170, v9
	v_cmp_gt_u32_e32 vcc, s6, v3
	v_cmp_lt_i32_e64 s[0:1], s3, v2
	v_pk_mul_f32 v[2:3], v[170:171], v[210:211]
	s_and_b64 vcc, vcc, s[0:1]
	v_sub_f32_e32 v2, v2, v3
	v_cndmask_b32_e32 v9, v243, v2, vcc
	v_or_b32_e32 v2, 18, v16
	v_sub_u32_e32 v3, v167, v2
	v_cvt_f32_i32_e32 v211, v3
	v_lshlrev_b32_e32 v2, s30, v2
	v_mov_b32_e32 v170, v10
	v_cmp_gt_u32_e32 vcc, s6, v3
	v_cmp_lt_i32_e64 s[0:1], s3, v2
	v_pk_mul_f32 v[2:3], v[170:171], v[210:211]
	s_and_b64 vcc, vcc, s[0:1]
	v_sub_f32_e32 v2, v2, v3
	v_cndmask_b32_e32 v10, v243, v2, vcc
	v_or_b32_e32 v2, 19, v16
	v_sub_u32_e32 v3, v167, v2
	v_cvt_f32_i32_e32 v211, v3
	v_lshlrev_b32_e32 v2, s30, v2
	v_mov_b32_e32 v170, v11
	v_cmp_gt_u32_e32 vcc, s6, v3
	v_cmp_lt_i32_e64 s[0:1], s3, v2
	v_pk_mul_f32 v[2:3], v[170:171], v[210:211]
	s_and_b64 vcc, vcc, s[0:1]
	v_sub_f32_e32 v2, v2, v3
	v_cndmask_b32_e32 v11, v243, v2, vcc
	v_or_b32_e32 v2, 24, v16
	v_sub_u32_e32 v3, v167, v2
	v_cvt_f32_i32_e32 v211, v3
	v_lshlrev_b32_e32 v2, s30, v2
	v_mov_b32_e32 v170, v12
	v_cmp_gt_u32_e32 vcc, s6, v3
	v_cmp_lt_i32_e64 s[0:1], s3, v2
	v_pk_mul_f32 v[2:3], v[170:171], v[210:211]
	s_and_b64 vcc, vcc, s[0:1]
	v_sub_f32_e32 v2, v2, v3
	v_cndmask_b32_e32 v12, v243, v2, vcc
	v_or_b32_e32 v2, 25, v16
	v_sub_u32_e32 v3, v167, v2
	v_cvt_f32_i32_e32 v211, v3
	v_lshlrev_b32_e32 v2, s30, v2
	v_mov_b32_e32 v170, v13
	v_cmp_gt_u32_e32 vcc, s6, v3
	v_cmp_lt_i32_e64 s[0:1], s3, v2
	v_pk_mul_f32 v[2:3], v[170:171], v[210:211]
	s_and_b64 vcc, vcc, s[0:1]
	v_sub_f32_e32 v2, v2, v3
	v_cndmask_b32_e32 v13, v243, v2, vcc
	v_or_b32_e32 v2, 26, v16
	v_sub_u32_e32 v3, v167, v2
	v_cvt_f32_i32_e32 v211, v3
	v_lshlrev_b32_e32 v2, s30, v2
	v_mov_b32_e32 v170, v14
	v_cmp_gt_u32_e32 vcc, s6, v3
	v_cmp_lt_i32_e64 s[0:1], s3, v2
	v_pk_mul_f32 v[2:3], v[170:171], v[210:211]
	s_and_b64 vcc, vcc, s[0:1]
	v_sub_f32_e32 v2, v2, v3
	v_cndmask_b32_e32 v14, v243, v2, vcc
	v_or_b32_e32 v2, 27, v16
	v_sub_u32_e32 v3, v167, v2
	v_cvt_f32_i32_e32 v211, v3
	v_lshlrev_b32_e32 v2, s30, v2
	v_mov_b32_e32 v170, v15
	v_cmp_gt_u32_e32 vcc, s6, v3
	v_cmp_lt_i32_e64 s[0:1], s3, v2
	v_pk_mul_f32 v[2:3], v[170:171], v[210:211]
	s_and_b64 vcc, vcc, s[0:1]
	v_sub_f32_e32 v2, v2, v3
	v_cndmask_b32_e32 v2, v243, v2, vcc
.Ldil_join_0:
	v_max_f32_e32 v20, v14, v2
	v_max_f32_e32 v3, v17, v19
	v_max_f32_e32 v15, v6, v7
	v_max_f32_e32 v16, v8, v9
	v_max_f32_e32 v18, v10, v11
	v_max3_f32 v20, v12, v13, v20
	v_max3_f32 v3, v0, v1, v3
	v_max3_f32 v15, v4, v5, v15
	v_max3_f32 v16, v16, v18, v20
	v_max3_f32 v3, v3, v15, v16
	v_mov_b32_e32 v15, v3
	s_nop 1
	v_permlane32_swap_b32_e32 v3, v15
	s_mov_b32 s0, 0xf149f2ca
	v_max3_f32 v144, v3, v15, s0
	v_sub_f32_e32 v0, v0, v144
	v_exp_f32_e32 v16, v0
	v_sub_f32_e32 v0, v1, v144
	v_exp_f32_e32 v18, v0
	v_sub_f32_e32 v0, v17, v144
	v_exp_f32_e32 v20, v0
	v_sub_f32_e32 v0, v19, v144
	v_exp_f32_e32 v22, v0
	v_sub_f32_e32 v0, v4, v144
	v_exp_f32_e32 v24, v0
	v_sub_f32_e32 v0, v5, v144
	v_exp_f32_e32 v26, v0
	v_sub_f32_e32 v0, v6, v144
	v_exp_f32_e32 v28, v0
	v_sub_f32_e32 v0, v7, v144
	v_exp_f32_e32 v30, v0
	v_sub_f32_e32 v0, v8, v144
	v_exp_f32_e32 v17, v0
	v_sub_f32_e32 v0, v9, v144
	v_exp_f32_e32 v19, v0
	v_sub_f32_e32 v0, v10, v144
	v_exp_f32_e32 v21, v0
	v_sub_f32_e32 v0, v11, v144
	v_exp_f32_e32 v23, v0
	v_sub_f32_e32 v0, v12, v144
	v_exp_f32_e32 v25, v0
	v_sub_f32_e32 v0, v13, v144
	v_exp_f32_e32 v27, v0
	v_sub_f32_e32 v0, v14, v144
	v_exp_f32_e32 v29, v0
	v_sub_f32_e32 v0, v2, v144
	v_exp_f32_e32 v31, v0
	v_sub_f32_e32 v3, 0xf149f2ca, v144
	v_exp_f32_e32 v76, v3
	v_pk_add_f32 v[0:1], v[16:17], v[18:19]
	v_pk_add_f32 v[2:3], v[20:21], v[22:23]
	v_pk_add_f32 v[4:5], v[28:29], v[30:31]
	v_pk_add_f32 v[0:1], v[0:1], v[2:3]
	v_pk_add_f32 v[2:3], v[24:25], v[26:27]
	s_cmp_lt_i32 s8, s31
	v_pk_add_f32 v[2:3], v[2:3], v[4:5]
	s_nop 0
	v_pk_add_f32 v[0:1], v[0:1], v[2:3]
	s_nop 0
	v_add_f32_e32 v145, v0, v1
	v_mul_f32_e32 v0, 0, v76
	v_fmac_f32_e32 v145, 0, v76
	v_cvt_pk_bf16_f32 v76, v16, v18
	v_cvt_pk_bf16_f32 v77, v20, v22
	v_cvt_pk_bf16_f32 v78, v24, v26
	v_cvt_pk_bf16_f32 v79, v28, v30
	v_cvt_pk_bf16_f32 v80, v17, v19
	v_cvt_pk_bf16_f32 v81, v21, v23
	v_cvt_pk_bf16_f32 v82, v25, v27
	v_cvt_pk_bf16_f32 v83, v29, v31
	s_waitcnt lgkmcnt(0)
	ds_read_b64_tr_b16 v[84:85], v179
	ds_read_b64_tr_b16 v[86:87], v179 offset:512
	v_mov_b32_e32 v1, v0
	v_mov_b32_e32 v2, v0
	v_mov_b32_e32 v3, v0
	v_mov_b32_e32 v4, v0
	v_mov_b32_e32 v5, v0
	v_mov_b32_e32 v6, v0
	v_mov_b32_e32 v7, v0
	v_mov_b32_e32 v8, v0
	v_mov_b32_e32 v9, v0
	v_mov_b32_e32 v10, v0
	v_mov_b32_e32 v11, v0
	v_mov_b32_e32 v12, v0
	v_mov_b32_e32 v13, v0
	v_mov_b32_e32 v14, v0
	v_mov_b32_e32 v15, v0
	s_waitcnt lgkmcnt(0)
	s_nop 0
	v_mfma_f32_32x32x16_bf16 v[16:31], v[84:87], v[76:79], v[0:15]
	ds_read_b64_tr_b16 v[84:85], v179 offset:1024
	ds_read_b64_tr_b16 v[86:87], v179 offset:1536
	s_waitcnt lgkmcnt(0)
	v_mfma_f32_32x32x16_bf16 v[16:31], v[84:87], v[80:83], v[16:31]
	ds_read_b64_tr_b16 v[84:85], v179 offset:2048
	ds_read_b64_tr_b16 v[86:87], v179 offset:2560
	s_waitcnt lgkmcnt(0)
	v_mfma_f32_32x32x16_bf16 v[0:15], v[84:87], v[76:79], v[0:15]
	ds_read_b64_tr_b16 v[76:77], v179 offset:3072
	ds_read_b64_tr_b16 v[78:79], v179 offset:3584
	s_waitcnt lgkmcnt(0)
	v_mfma_f32_32x32x16_bf16 v[0:15], v[76:79], v[80:83], v[0:15]
	s_cbranch_scc1 .LBB0_1255
	s_mov_b32 s0, 1
	s_lshl_b32 s0, s0, 5
	s_add_i32 s9, s0, 0xffffff80
	v_or_b32_e32 v108, s9, v176
	v_or_b32_e32 v76, s9, v167
	v_lshlrev_b32_e32 v96, s30, v108
	v_or_b32_e32 v100, 8, v108
	v_or_b32_e32 v104, 16, v108
	v_or_b32_e32 v108, 24, v108
	v_lshlrev_b32_e32 v76, s30, v76
	v_lshlrev_b32_e32 v100, s30, v100
	v_lshlrev_b32_e32 v104, s30, v104
	v_lshlrev_b32_e32 v108, s30, v108
	v_add_u32_e32 v76, s8, v76
	v_add_u32_e32 v96, s8, v96
	v_add_u32_e32 v100, s8, v100
	v_add_u32_e32 v104, s8, v104
	v_add_u32_e32 v108, s8, v108
	v_max_i32_e32 v76, 0, v76
	v_max_i32_e32 v96, 0, v96
	v_max_i32_e32 v100, 0, v100
	v_max_i32_e32 v104, 0, v104
	v_max_i32_e32 v108, 0, v108
	v_add_u32_e32 v76, s18, v76
	v_add_u32_e32 v96, s18, v96
	v_add_u32_e32 v100, s18, v100
	v_add_u32_e32 v104, s18, v104
	v_add_u32_e32 v108, s18, v108
	v_mad_u64_u32 v[88:89], s[0:1], v76, s81, v[162:163]
	v_mad_u64_u32 v[96:97], s[0:1], v96, s81, v[164:165]
	v_mad_u64_u32 v[100:101], s[0:1], v100, s81, v[164:165]
	v_mad_u64_u32 v[104:105], s[0:1], v104, s81, v[164:165]
	v_mad_u64_u32 v[108:109], s[0:1], v108, s81, v[164:165]
	s_mov_b32 s0, 3
	global_load_dwordx4 v[76:79], v[88:89], off
	global_load_dwordx4 v[80:83], v[88:89], off offset:32
	global_load_dwordx4 v[84:87], v[88:89], off offset:64
	s_nop 0
	global_load_dwordx4 v[88:91], v[88:89], off offset:96
	s_nop 0
	global_load_dwordx4 v[96:99], v[96:97], off
	s_nop 0
	global_load_dwordx4 v[100:103], v[100:101], off
	s_nop 0
	global_load_dwordx4 v[104:107], v[104:105], off
	s_nop 0
	global_load_dwordx4 v[108:111], v[108:109], off
	s_waitcnt lgkmcnt(0)
	s_waitcnt vmcnt(19)
	ds_write_b128 v178, v[36:39]
	s_waitcnt vmcnt(18)
	ds_write_b128 v178, v[40:43] offset:512
	s_waitcnt vmcnt(17)
	ds_write_b128 v178, v[44:47] offset:1024
	s_waitcnt vmcnt(16)
	ds_write_b128 v178, v[136:139] offset:1536
	v_mfma_f32_32x32x16_bf16 v[32:47], v[32:35], v[48:51], 0
	v_mfma_f32_32x32x16_bf16 v[32:47], v[132:135], v[52:55], v[32:47]
	v_mfma_f32_32x32x16_bf16 v[32:47], v[128:131], v[56:59], v[32:47]
	v_mfma_f32_32x32x16_bf16 v[32:47], v[124:127], v[60:63], v[32:47]
	v_lshl_add_u32 v124, s0, 5, v177
	v_sub_u32_e32 v211, v167, v124
	v_add_u32_e32 v170, 0xffffffe5, v211
	v_cmp_le_u32_e32 vcc, 0x66, v170
	v_lshlrev_b32_e32 v170, s30, v124
	s_nop 2
	s_cbranch_vccnz .Ldil_slow_1
	v_cmp_ge_i32_e32 vcc, s3, v170
	s_nop 3
	s_cbranch_vccnz .Ldil_slow_1
	v_cvt_f32_i32_e32 v170, v211
	v_mul_f32_e32 v170, v171, v170
	v_fma_f32 v32, v32, v210, -v170
	v_fma_f32 v33, v33, v210, -v170
	v_fmamk_f32 v33, v171, 0x3f800000, v33
	v_fma_f32 v125, v34, v210, -v170
	v_fmamk_f32 v125, v171, 0x40000000, v125
	v_fma_f32 v126, v35, v210, -v170
	v_fmamk_f32 v126, v171, 0x40400000, v126
	v_fma_f32 v127, v36, v210, -v170
	v_fmamk_f32 v127, v171, 0x41000000, v127
	v_fma_f32 v37, v37, v210, -v170
	v_fmamk_f32 v37, v171, 0x41100000, v37
	v_fma_f32 v128, v38, v210, -v170
	v_fmamk_f32 v128, v171, 0x41200000, v128
	v_fma_f32 v39, v39, v210, -v170
	v_fmamk_f32 v39, v171, 0x41300000, v39
	v_fma_f32 v129, v40, v210, -v170
	v_fmamk_f32 v129, v171, 0x41800000, v129
	v_fma_f32 v41, v41, v210, -v170
	v_fmamk_f32 v41, v171, 0x41880000, v41
	v_fma_f32 v130, v42, v210, -v170
	v_fmamk_f32 v130, v171, 0x41900000, v130
	v_fma_f32 v43, v43, v210, -v170
	v_fmamk_f32 v43, v171, 0x41980000, v43
	v_fma_f32 v131, v44, v210, -v170
	v_fmamk_f32 v131, v171, 0x41c00000, v131
	v_fma_f32 v132, v45, v210, -v170
	v_fmamk_f32 v132, v171, 0x41c80000, v132
	v_fma_f32 v133, v46, v210, -v170
	v_fmamk_f32 v133, v171, 0x41d00000, v133
	v_fma_f32 v34, v47, v210, -v170
	v_fmamk_f32 v34, v171, 0x41d80000, v34
	s_branch .Ldil_join_1

.Ldil_join_1:
	v_max_f32_e32 v42, v133, v34
	v_max_f32_e32 v35, v125, v126
	v_max_f32_e32 v36, v128, v39
	v_max_f32_e32 v38, v129, v41
	v_max_f32_e32 v40, v130, v43
	v_max3_f32 v42, v131, v132, v42
	v_max3_f32 v35, v32, v33, v35
	v_max3_f32 v36, v127, v37, v36
	v_max3_f32 v38, v38, v40, v42
	v_max3_f32 v35, v35, v36, v38
	v_mov_b32_e32 v36, v35
	s_nop 1
	v_permlane32_swap_b32_e32 v35, v36
	v_max3_f32 v181, v144, v35, v36
	v_sub_f32_e32 v32, v32, v181
	v_exp_f32_e32 v36, v32
	v_sub_f32_e32 v32, v33, v181
	v_exp_f32_e32 v38, v32
	v_sub_f32_e32 v32, v125, v181
	v_exp_f32_e32 v40, v32
	v_sub_f32_e32 v32, v126, v181
	v_exp_f32_e32 v42, v32
	v_sub_f32_e32 v32, v127, v181
	v_exp_f32_e32 v44, v32
	v_sub_f32_e32 v32, v37, v181
	v_exp_f32_e32 v46, v32
	v_sub_f32_e32 v32, v128, v181
	v_exp_f32_e32 v124, v32
	v_sub_f32_e32 v32, v39, v181
	v_exp_f32_e32 v126, v32
	v_sub_f32_e32 v32, v129, v181
	v_exp_f32_e32 v37, v32
	v_sub_f32_e32 v32, v41, v181
	v_exp_f32_e32 v39, v32
	v_sub_f32_e32 v32, v130, v181
	v_exp_f32_e32 v41, v32
	v_sub_f32_e32 v32, v43, v181
	v_exp_f32_e32 v43, v32
	v_sub_f32_e32 v32, v131, v181
	v_exp_f32_e32 v45, v32
	v_sub_f32_e32 v32, v132, v181
	v_exp_f32_e32 v47, v32
	v_sub_f32_e32 v32, v133, v181
	v_exp_f32_e32 v125, v32
	v_sub_f32_e32 v32, v34, v181
	v_exp_f32_e32 v127, v32
	v_sub_f32_e32 v35, v144, v181
	v_exp_f32_e32 v32, v35
	v_pk_add_f32 v[34:35], v[36:37], v[38:39]
	v_pk_add_f32 v[128:129], v[40:41], v[42:43]
	v_pk_add_f32 v[130:131], v[124:125], v[126:127]
	v_pk_add_f32 v[34:35], v[34:35], v[128:129]
	v_pk_add_f32 v[128:129], v[44:45], v[46:47]
	v_pk_mul_f32 v[30:31], v[30:31], v[32:33] op_sel_hi:[1,0]
	v_pk_add_f32 v[128:129], v[128:129], v[130:131]
	v_pk_mul_f32 v[28:29], v[28:29], v[32:33] op_sel_hi:[1,0]
	v_pk_add_f32 v[34:35], v[34:35], v[128:129]
	v_pk_mul_f32 v[26:27], v[26:27], v[32:33] op_sel_hi:[1,0]
	v_add_f32_e32 v175, v34, v35
	v_pk_mul_f32 v[24:25], v[24:25], v[32:33] op_sel_hi:[1,0]
	v_pk_mul_f32 v[22:23], v[22:23], v[32:33] op_sel_hi:[1,0]
	v_pk_mul_f32 v[20:21], v[20:21], v[32:33] op_sel_hi:[1,0]
	v_pk_mul_f32 v[18:19], v[18:19], v[32:33] op_sel_hi:[1,0]
	v_pk_mul_f32 v[16:17], v[16:17], v[32:33] op_sel_hi:[1,0]
	v_pk_mul_f32 v[14:15], v[14:15], v[32:33] op_sel_hi:[1,0]
	v_pk_mul_f32 v[12:13], v[12:13], v[32:33] op_sel_hi:[1,0]
	v_pk_mul_f32 v[10:11], v[10:11], v[32:33] op_sel_hi:[1,0]
	v_pk_mul_f32 v[8:9], v[8:9], v[32:33] op_sel_hi:[1,0]
	v_pk_mul_f32 v[6:7], v[6:7], v[32:33] op_sel_hi:[1,0]
	v_pk_mul_f32 v[4:5], v[4:5], v[32:33] op_sel_hi:[1,0]
	v_pk_mul_f32 v[2:3], v[2:3], v[32:33] op_sel_hi:[1,0]
	v_pk_mul_f32 v[0:1], v[0:1], v[32:33] op_sel_hi:[1,0]
	v_fmac_f32_e32 v175, v145, v32
	v_cvt_pk_bf16_f32 v32, v36, v38
	v_cvt_pk_bf16_f32 v33, v40, v42
	v_cvt_pk_bf16_f32 v34, v44, v46
	v_cvt_pk_bf16_f32 v35, v124, v126
	v_cvt_pk_bf16_f32 v36, v37, v39
	v_cvt_pk_bf16_f32 v37, v41, v43
	v_cvt_pk_bf16_f32 v38, v45, v47
	v_cvt_pk_bf16_f32 v39, v125, v127
	s_waitcnt lgkmcnt(0)
	ds_read_b64_tr_b16 v[40:41], v179
	ds_read_b64_tr_b16 v[42:43], v179 offset:512
	s_waitcnt lgkmcnt(0)
	v_mfma_f32_32x32x16_bf16 v[16:31], v[40:43], v[32:35], v[16:31]
	ds_read_b64_tr_b16 v[40:41], v179 offset:1024
	ds_read_b64_tr_b16 v[42:43], v179 offset:1536
	s_cmp_lt_i32 s8, s35
	s_waitcnt lgkmcnt(0)
	v_mfma_f32_32x32x16_bf16 v[16:31], v[40:43], v[36:39], v[16:31]
	ds_read_b64_tr_b16 v[40:41], v179 offset:2048
	ds_read_b64_tr_b16 v[42:43], v179 offset:2560
	s_waitcnt lgkmcnt(0)
	v_mfma_f32_32x32x16_bf16 v[0:15], v[40:43], v[32:35], v[0:15]
	ds_read_b64_tr_b16 v[32:33], v179 offset:3072
	ds_read_b64_tr_b16 v[34:35], v179 offset:3584
	s_waitcnt lgkmcnt(0)
	v_mfma_f32_32x32x16_bf16 v[0:15], v[32:35], v[36:39], v[0:15]
	s_cbranch_scc1 .LBB0_1254
	s_mov_b32 s0, s19
	s_lshl_b32 s0, s0, 5
	s_add_i32 s9, s0, 0xffffff80
	v_or_b32_e32 v32, s9, v167
	v_lshlrev_b32_e32 v32, s30, v32
	v_add_u32_e32 v32, s8, v32
	v_max_i32_e32 v32, 0, v32
	v_add_u32_e32 v32, s18, v32
	v_mad_u64_u32 v[32:33], s[0:1], v32, s81, v[162:163]
	v_or_b32_e32 v34, s9, v176
	global_load_dwordx4 v[124:127], v[32:33], off
	global_load_dwordx4 v[128:131], v[32:33], off offset:32
	global_load_dwordx4 v[132:135], v[32:33], off offset:64
	global_load_dwordx4 v[136:139], v[32:33], off offset:96
	v_lshlrev_b32_e32 v32, s30, v34
	v_add_u32_e32 v32, s8, v32
	v_max_i32_e32 v32, 0, v32
	v_add_u32_e32 v32, s18, v32
	v_mad_u64_u32 v[32:33], s[0:1], v32, s81, v[164:165]
	global_load_dwordx4 v[144:147], v[32:33], off
	v_or_b32_e32 v32, 8, v34
	v_lshlrev_b32_e32 v32, s30, v32
	v_add_u32_e32 v32, s8, v32
	v_max_i32_e32 v32, 0, v32
	v_add_u32_e32 v32, s18, v32
	v_mad_u64_u32 v[32:33], s[0:1], v32, s81, v[164:165]
	global_load_dwordx4 v[148:151], v[32:33], off
	v_or_b32_e32 v32, 16, v34
	v_lshlrev_b32_e32 v32, s30, v32
	v_add_u32_e32 v32, s8, v32
	v_max_i32_e32 v32, 0, v32
	v_add_u32_e32 v32, s18, v32
	v_mad_u64_u32 v[32:33], s[0:1], v32, s81, v[164:165]
	global_load_dwordx4 v[152:155], v[32:33], off
	v_or_b32_e32 v32, 24, v34
	v_lshlrev_b32_e32 v32, s30, v32
	v_add_u32_e32 v32, s8, v32
	v_max_i32_e32 v32, 0, v32
	v_add_u32_e32 v32, s18, v32
	v_mad_u64_u32 v[32:33], s[0:1], v32, s81, v[164:165]
	global_load_dwordx4 v[156:159], v[32:33], off
	s_waitcnt vmcnt(23)
	v_mfma_f32_32x32x16_bf16 v[32:47], v[92:95], v[48:51], 0
	s_mov_b32 s0, 2
	s_waitcnt lgkmcnt(0)
	s_waitcnt vmcnt(19)
	ds_write_b128 v178, v[112:115]
	s_waitcnt vmcnt(18)
	ds_write_b128 v178, v[116:119] offset:512
	s_waitcnt vmcnt(17)
	ds_write_b128 v178, v[120:123] offset:1024
	s_waitcnt vmcnt(16)
	ds_write_b128 v178, v[140:143] offset:1536
	v_mfma_f32_32x32x16_bf16 v[32:47], v[72:75], v[52:55], v[32:47]
	v_mfma_f32_32x32x16_bf16 v[32:47], v[68:71], v[56:59], v[32:47]
	v_mfma_f32_32x32x16_bf16 v[32:47], v[64:67], v[60:63], v[32:47]
	v_lshl_add_u32 v64, s0, 5, v177
	v_sub_u32_e32 v211, v167, v64
	v_add_u32_e32 v170, 0xffffffe5, v211
	v_cmp_le_u32_e32 vcc, 0x66, v170
	v_lshlrev_b32_e32 v170, s30, v64
	s_nop 2
	s_cbranch_vccnz .Ldil_slow_2
	v_cmp_ge_i32_e32 vcc, s3, v170
	s_nop 3
	s_cbranch_vccnz .Ldil_slow_2
	v_cvt_f32_i32_e32 v170, v211
	v_mul_f32_e32 v170, v171, v170
	v_fma_f32 v32, v32, v210, -v170
	v_fma_f32 v33, v33, v210, -v170
	v_fmamk_f32 v33, v171, 0x3f800000, v33
	v_fma_f32 v65, v34, v210, -v170
	v_fmamk_f32 v65, v171, 0x40000000, v65
	v_fma_f32 v66, v35, v210, -v170
	v_fmamk_f32 v66, v171, 0x40400000, v66
	v_fma_f32 v68, v36, v210, -v170
	v_fmamk_f32 v68, v171, 0x41000000, v68
	v_fma_f32 v37, v37, v210, -v170
	v_fmamk_f32 v37, v171, 0x41100000, v37
	v_fma_f32 v69, v38, v210, -v170
	v_fmamk_f32 v69, v171, 0x41200000, v69
	v_fma_f32 v39, v39, v210, -v170
	v_fmamk_f32 v39, v171, 0x41300000, v39
	v_fma_f32 v71, v40, v210, -v170
	v_fmamk_f32 v71, v171, 0x41800000, v71
	v_fma_f32 v41, v41, v210, -v170
	v_fmamk_f32 v41, v171, 0x41880000, v41
	v_fma_f32 v72, v42, v210, -v170
	v_fmamk_f32 v72, v171, 0x41900000, v72
	v_fma_f32 v43, v43, v210, -v170
	v_fmamk_f32 v43, v171, 0x41980000, v43
	v_fma_f32 v73, v44, v210, -v170
	v_fmamk_f32 v73, v171, 0x41c00000, v73
	v_fma_f32 v74, v45, v210, -v170
	v_fmamk_f32 v74, v171, 0x41c80000, v74
	v_fma_f32 v75, v46, v210, -v170
	v_fmamk_f32 v75, v171, 0x41d00000, v75
	v_fma_f32 v34, v47, v210, -v170
	v_fmamk_f32 v34, v171, 0x41d80000, v34
	s_branch .Ldil_join_2

.Ldil_join_2:
	v_max_f32_e32 v42, v75, v34
	v_max_f32_e32 v35, v65, v66
	v_max_f32_e32 v36, v69, v39
	v_max_f32_e32 v38, v71, v41
	v_max_f32_e32 v40, v72, v43
	v_max3_f32 v42, v73, v74, v42
	v_max3_f32 v35, v32, v33, v35
	v_max3_f32 v36, v68, v37, v36
	v_max3_f32 v38, v38, v40, v42
	v_max3_f32 v35, v35, v36, v38
	v_mov_b32_e32 v36, v35
	s_nop 1
	v_permlane32_swap_b32_e32 v35, v36
	v_max3_f32 v67, v181, v35, v36
	v_sub_f32_e32 v32, v32, v67
	v_exp_f32_e32 v36, v32
	v_sub_f32_e32 v32, v33, v67
	v_exp_f32_e32 v38, v32
	v_sub_f32_e32 v32, v65, v67
	v_exp_f32_e32 v40, v32
	v_sub_f32_e32 v32, v66, v67
	v_exp_f32_e32 v42, v32
	v_sub_f32_e32 v32, v68, v67
	v_exp_f32_e32 v44, v32
	v_sub_f32_e32 v32, v37, v67
	v_exp_f32_e32 v46, v32
	v_sub_f32_e32 v32, v69, v67
	v_exp_f32_e32 v68, v32
	v_sub_f32_e32 v32, v39, v67
	v_exp_f32_e32 v70, v32
	v_sub_f32_e32 v32, v71, v67
	v_exp_f32_e32 v37, v32
	v_sub_f32_e32 v32, v41, v67
	v_exp_f32_e32 v39, v32
	v_sub_f32_e32 v32, v72, v67
	v_exp_f32_e32 v41, v32
	v_sub_f32_e32 v32, v43, v67
	v_exp_f32_e32 v43, v32
	v_sub_f32_e32 v32, v73, v67
	v_exp_f32_e32 v45, v32
	v_sub_f32_e32 v32, v74, v67
	v_exp_f32_e32 v47, v32
	v_sub_f32_e32 v32, v75, v67
	v_exp_f32_e32 v69, v32
	v_sub_f32_e32 v32, v34, v67
	v_exp_f32_e32 v71, v32
	v_sub_f32_e32 v35, v181, v67
	v_exp_f32_e32 v32, v35
	v_pk_add_f32 v[34:35], v[36:37], v[38:39]
	v_pk_add_f32 v[64:65], v[40:41], v[42:43]
	v_pk_add_f32 v[72:73], v[68:69], v[70:71]
	v_pk_add_f32 v[34:35], v[34:35], v[64:65]
	v_pk_add_f32 v[64:65], v[44:45], v[46:47]
	v_pk_mul_f32 v[30:31], v[30:31], v[32:33] op_sel_hi:[1,0]
	v_pk_add_f32 v[64:65], v[64:65], v[72:73]
	v_pk_mul_f32 v[28:29], v[28:29], v[32:33] op_sel_hi:[1,0]
	v_pk_add_f32 v[34:35], v[34:35], v[64:65]
	v_pk_mul_f32 v[26:27], v[26:27], v[32:33] op_sel_hi:[1,0]
	v_add_f32_e32 v65, v34, v35
	v_pk_mul_f32 v[24:25], v[24:25], v[32:33] op_sel_hi:[1,0]
	v_pk_mul_f32 v[22:23], v[22:23], v[32:33] op_sel_hi:[1,0]
	v_pk_mul_f32 v[20:21], v[20:21], v[32:33] op_sel_hi:[1,0]
	v_pk_mul_f32 v[18:19], v[18:19], v[32:33] op_sel_hi:[1,0]
	v_pk_mul_f32 v[16:17], v[16:17], v[32:33] op_sel_hi:[1,0]
	v_pk_mul_f32 v[14:15], v[14:15], v[32:33] op_sel_hi:[1,0]
	v_pk_mul_f32 v[12:13], v[12:13], v[32:33] op_sel_hi:[1,0]
	v_pk_mul_f32 v[10:11], v[10:11], v[32:33] op_sel_hi:[1,0]
	v_pk_mul_f32 v[8:9], v[8:9], v[32:33] op_sel_hi:[1,0]
	v_pk_mul_f32 v[6:7], v[6:7], v[32:33] op_sel_hi:[1,0]
	v_pk_mul_f32 v[4:5], v[4:5], v[32:33] op_sel_hi:[1,0]
	v_pk_mul_f32 v[2:3], v[2:3], v[32:33] op_sel_hi:[1,0]
	v_pk_mul_f32 v[0:1], v[0:1], v[32:33] op_sel_hi:[1,0]
	v_fmac_f32_e32 v65, v175, v32
	v_cvt_pk_bf16_f32 v32, v36, v38
	v_cvt_pk_bf16_f32 v33, v40, v42
	v_cvt_pk_bf16_f32 v34, v44, v46
	v_cvt_pk_bf16_f32 v35, v68, v70
	v_cvt_pk_bf16_f32 v36, v37, v39
	v_cvt_pk_bf16_f32 v37, v41, v43
	v_cvt_pk_bf16_f32 v38, v45, v47
	v_cvt_pk_bf16_f32 v39, v69, v71
	s_waitcnt lgkmcnt(0)
	ds_read_b64_tr_b16 v[40:41], v179
	ds_read_b64_tr_b16 v[42:43], v179 offset:512
	s_waitcnt lgkmcnt(0)
	v_mfma_f32_32x32x16_bf16 v[16:31], v[40:43], v[32:35], v[16:31]
	ds_read_b64_tr_b16 v[40:41], v179 offset:1024
	ds_read_b64_tr_b16 v[42:43], v179 offset:1536
	s_cmp_lt_i32 s8, s50
	s_waitcnt lgkmcnt(0)
	v_mfma_f32_32x32x16_bf16 v[16:31], v[40:43], v[36:39], v[16:31]
	ds_read_b64_tr_b16 v[40:41], v179 offset:2048
	ds_read_b64_tr_b16 v[42:43], v179 offset:2560
	s_waitcnt lgkmcnt(0)
	v_mfma_f32_32x32x16_bf16 v[0:15], v[40:43], v[32:35], v[0:15]
	ds_read_b64_tr_b16 v[32:33], v179 offset:3072
	ds_read_b64_tr_b16 v[34:35], v179 offset:3584
	s_waitcnt lgkmcnt(0)
	v_mfma_f32_32x32x16_bf16 v[0:15], v[32:35], v[36:39], v[0:15]
	s_cbranch_scc1 .LBB0_1253
	s_waitcnt vmcnt(15)
	v_mfma_f32_32x32x16_bf16 v[32:47], v[76:79], v[48:51], 0
	s_mov_b32 s0, 1
	s_waitcnt lgkmcnt(0)
	s_waitcnt vmcnt(11)
	ds_write_b128 v178, v[96:99]
	s_waitcnt vmcnt(10)
	ds_write_b128 v178, v[100:103] offset:512
	s_waitcnt vmcnt(9)
	ds_write_b128 v178, v[104:107] offset:1024
	s_waitcnt vmcnt(8)
	ds_write_b128 v178, v[108:111] offset:1536
	v_lshl_add_u32 v64, s0, 5, v177
	v_sub_u32_e32 v66, v167, v64
	v_cvt_f32_i32_e32 v211, v66
	v_mfma_f32_32x32x16_bf16 v[32:47], v[80:83], v[52:55], v[32:47]
	v_lshlrev_b32_e32 v68, s30, v64
	v_cmp_gt_u32_e32 vcc, s6, v66
	v_cmp_lt_i32_e64 s[0:1], s3, v68
	v_or_b32_e32 v66, 1, v64
	s_and_b64 vcc, vcc, s[0:1]
	v_mfma_f32_32x32x16_bf16 v[32:47], v[84:87], v[56:59], v[32:47]
	v_mfma_f32_32x32x16_bf16 v[32:47], v[88:91], v[60:63], v[32:47]
	s_nop 11
	v_sub_u32_e32 v211, v167, v64
	v_add_u32_e32 v170, 0xffffffe5, v211
	v_cmp_le_u32_e32 vcc, 0x66, v170
	v_lshlrev_b32_e32 v170, s30, v64
	s_nop 2
	s_cbranch_vccnz .Ldil_slow_3
	v_cmp_ge_i32_e32 vcc, s3, v170
	s_nop 3
	s_cbranch_vccnz .Ldil_slow_3
	v_cvt_f32_i32_e32 v170, v211
	v_mul_f32_e32 v170, v171, v170
	v_fma_f32 v32, v32, v210, -v170
	v_fma_f32 v33, v33, v210, -v170
	v_fmamk_f32 v33, v171, 0x3f800000, v33
	v_fma_f32 v68, v34, v210, -v170
	v_fmamk_f32 v68, v171, 0x40000000, v68
	v_fma_f32 v69, v35, v210, -v170
	v_fmamk_f32 v69, v171, 0x40400000, v69
	v_fma_f32 v70, v36, v210, -v170
	v_fmamk_f32 v70, v171, 0x41000000, v70
	v_fma_f32 v37, v37, v210, -v170
	v_fmamk_f32 v37, v171, 0x41100000, v37
	v_fma_f32 v71, v38, v210, -v170
	v_fmamk_f32 v71, v171, 0x41200000, v71
	v_fma_f32 v39, v39, v210, -v170
	v_fmamk_f32 v39, v171, 0x41300000, v39
	v_fma_f32 v72, v40, v210, -v170
	v_fmamk_f32 v72, v171, 0x41800000, v72
	v_fma_f32 v41, v41, v210, -v170
	v_fmamk_f32 v41, v171, 0x41880000, v41
	v_fma_f32 v73, v42, v210, -v170
	v_fmamk_f32 v73, v171, 0x41900000, v73
	v_fma_f32 v43, v43, v210, -v170
	v_fmamk_f32 v43, v171, 0x41980000, v43
	v_fma_f32 v74, v44, v210, -v170
	v_fmamk_f32 v74, v171, 0x41c00000, v74
	v_fma_f32 v75, v45, v210, -v170
	v_fmamk_f32 v75, v171, 0x41c80000, v75
	v_fma_f32 v76, v46, v210, -v170
	v_fmamk_f32 v76, v171, 0x41d00000, v76
	v_fma_f32 v34, v47, v210, -v170
	v_fmamk_f32 v34, v171, 0x41d80000, v34
	s_branch .Ldil_join_3

.Ldil_join_3:
	v_max_f32_e32 v42, v76, v34
	v_max_f32_e32 v35, v68, v69
	v_max_f32_e32 v36, v71, v39
	v_max_f32_e32 v38, v72, v41
	v_max_f32_e32 v40, v73, v43
	v_max3_f32 v42, v74, v75, v42
	v_max3_f32 v35, v32, v33, v35
	v_max3_f32 v36, v70, v37, v36
	v_max3_f32 v38, v38, v40, v42
	v_max3_f32 v35, v35, v36, v38
	v_mov_b32_e32 v36, v35
	s_nop 1
	v_permlane32_swap_b32_e32 v35, v36
	v_max3_f32 v66, v67, v35, v36
	v_sub_f32_e32 v32, v32, v66
	v_exp_f32_e32 v36, v32
	v_sub_f32_e32 v32, v33, v66
	v_exp_f32_e32 v38, v32
	v_sub_f32_e32 v32, v68, v66
	v_exp_f32_e32 v40, v32
	v_sub_f32_e32 v32, v69, v66
	v_exp_f32_e32 v42, v32
	v_sub_f32_e32 v32, v70, v66
	v_exp_f32_e32 v44, v32
	v_sub_f32_e32 v32, v37, v66
	v_exp_f32_e32 v46, v32
	v_sub_f32_e32 v32, v71, v66
	v_exp_f32_e32 v68, v32
	v_sub_f32_e32 v32, v39, v66
	v_exp_f32_e32 v70, v32
	v_sub_f32_e32 v32, v72, v66
	v_exp_f32_e32 v37, v32
	v_sub_f32_e32 v32, v41, v66
	v_exp_f32_e32 v39, v32
	v_sub_f32_e32 v32, v73, v66
	v_exp_f32_e32 v41, v32
	v_sub_f32_e32 v32, v43, v66
	v_exp_f32_e32 v43, v32
	v_sub_f32_e32 v32, v74, v66
	v_exp_f32_e32 v45, v32
	v_sub_f32_e32 v32, v75, v66
	v_exp_f32_e32 v47, v32
	v_sub_f32_e32 v32, v76, v66
	v_exp_f32_e32 v69, v32
	v_sub_f32_e32 v32, v34, v66
	v_exp_f32_e32 v71, v32
	v_sub_f32_e32 v35, v67, v66
	v_exp_f32_e32 v32, v35
	v_pk_add_f32 v[34:35], v[36:37], v[38:39]
	v_pk_add_f32 v[72:73], v[40:41], v[42:43]
	v_pk_add_f32 v[74:75], v[68:69], v[70:71]
	v_pk_add_f32 v[34:35], v[34:35], v[72:73]
	v_pk_add_f32 v[72:73], v[44:45], v[46:47]
	v_pk_mul_f32 v[30:31], v[30:31], v[32:33] op_sel_hi:[1,0]
	v_pk_add_f32 v[72:73], v[72:73], v[74:75]
	v_pk_mul_f32 v[28:29], v[28:29], v[32:33] op_sel_hi:[1,0]
	v_pk_add_f32 v[34:35], v[34:35], v[72:73]
	v_pk_mul_f32 v[26:27], v[26:27], v[32:33] op_sel_hi:[1,0]
	v_add_f32_e32 v64, v34, v35
	v_pk_mul_f32 v[24:25], v[24:25], v[32:33] op_sel_hi:[1,0]
	v_pk_mul_f32 v[22:23], v[22:23], v[32:33] op_sel_hi:[1,0]
	v_pk_mul_f32 v[20:21], v[20:21], v[32:33] op_sel_hi:[1,0]
	v_pk_mul_f32 v[18:19], v[18:19], v[32:33] op_sel_hi:[1,0]
	v_pk_mul_f32 v[16:17], v[16:17], v[32:33] op_sel_hi:[1,0]
	v_pk_mul_f32 v[14:15], v[14:15], v[32:33] op_sel_hi:[1,0]
	v_pk_mul_f32 v[12:13], v[12:13], v[32:33] op_sel_hi:[1,0]
	v_pk_mul_f32 v[10:11], v[10:11], v[32:33] op_sel_hi:[1,0]
	v_pk_mul_f32 v[8:9], v[8:9], v[32:33] op_sel_hi:[1,0]
	v_pk_mul_f32 v[6:7], v[6:7], v[32:33] op_sel_hi:[1,0]
	v_pk_mul_f32 v[4:5], v[4:5], v[32:33] op_sel_hi:[1,0]
	v_pk_mul_f32 v[2:3], v[2:3], v[32:33] op_sel_hi:[1,0]
	v_pk_mul_f32 v[0:1], v[0:1], v[32:33] op_sel_hi:[1,0]
	v_fmac_f32_e32 v64, v65, v32
	v_cvt_pk_bf16_f32 v32, v36, v38
	v_cvt_pk_bf16_f32 v33, v40, v42
	v_cvt_pk_bf16_f32 v34, v44, v46
	v_cvt_pk_bf16_f32 v35, v68, v70
	v_cvt_pk_bf16_f32 v36, v37, v39
	v_cvt_pk_bf16_f32 v37, v41, v43
	v_cvt_pk_bf16_f32 v38, v45, v47
	v_cvt_pk_bf16_f32 v39, v69, v71
	s_waitcnt lgkmcnt(0)
	ds_read_b64_tr_b16 v[40:41], v179
	ds_read_b64_tr_b16 v[42:43], v179 offset:512
	s_waitcnt lgkmcnt(0)
	v_mfma_f32_32x32x16_bf16 v[16:31], v[40:43], v[32:35], v[16:31]
	ds_read_b64_tr_b16 v[40:41], v179 offset:1024
	ds_read_b64_tr_b16 v[42:43], v179 offset:1536
	s_cmp_lt_i32 s8, s51
	s_waitcnt lgkmcnt(0)
	v_mfma_f32_32x32x16_bf16 v[16:31], v[40:43], v[36:39], v[16:31]
	ds_read_b64_tr_b16 v[40:41], v179 offset:2048
	ds_read_b64_tr_b16 v[42:43], v179 offset:2560
	s_waitcnt lgkmcnt(0)
	v_mfma_f32_32x32x16_bf16 v[0:15], v[40:43], v[32:35], v[0:15]
	ds_read_b64_tr_b16 v[32:33], v179 offset:3072
	ds_read_b64_tr_b16 v[34:35], v179 offset:3584
	s_waitcnt lgkmcnt(0)
	v_mfma_f32_32x32x16_bf16 v[0:15], v[32:35], v[36:39], v[0:15]
	s_cbranch_scc1 .LBB0_1252
	s_waitcnt vmcnt(7)
	v_mfma_f32_32x32x16_bf16 v[32:47], v[124:127], v[48:51], 0
	s_mov_b32 s0, s19
	s_waitcnt lgkmcnt(0)
	s_waitcnt vmcnt(3)
	ds_write_b128 v178, v[144:147]
	s_waitcnt vmcnt(2)
	ds_write_b128 v178, v[148:151] offset:512
	s_waitcnt vmcnt(1)
	ds_write_b128 v178, v[152:155] offset:1024
	s_waitcnt vmcnt(0)
	ds_write_b128 v178, v[156:159] offset:1536
	v_lshl_add_u32 v48, s0, 5, v177
	v_sub_u32_e32 v49, v167, v48
	v_cvt_f32_i32_e32 v211, v49
	v_mfma_f32_32x32x16_bf16 v[32:47], v[128:131], v[52:55], v[32:47]
	v_lshlrev_b32_e32 v50, s30, v48
	v_cmp_gt_u32_e32 vcc, s6, v49
	v_cmp_lt_i32_e64 s[0:1], s3, v50
	v_or_b32_e32 v49, 1, v48
	s_and_b64 vcc, vcc, s[0:1]
	v_mfma_f32_32x32x16_bf16 v[32:47], v[132:135], v[56:59], v[32:47]
	v_mfma_f32_32x32x16_bf16 v[32:47], v[136:139], v[60:63], v[32:47]
	s_nop 11
	v_sub_u32_e32 v211, v167, v48
	v_cmp_gt_i32_e32 vcc, 27, v211
	v_lshlrev_b32_e32 v170, s30, v48
	s_nop 2
	s_cbranch_vccnz .Ldil_slow_4
	v_cmp_ge_i32_e32 vcc, s3, v170
	s_nop 3
	s_cbranch_vccnz .Ldil_slow_4
	v_cvt_f32_i32_e32 v170, v211
	v_mul_f32_e32 v170, v171, v170
	v_add_u32_e32 v211, 0xffffff80, v211
	v_fma_f32 v32, v32, v210, -v170
	v_cmp_ge_i32_e32 vcc, 0, v211
	v_fma_f32 v33, v33, v210, -v170
	v_fmamk_f32 v33, v171, 0x3f800000, v33
	v_cndmask_b32_e32 v32, v243, v32, vcc
	v_cmp_ge_i32_e32 vcc, 1, v211
	v_fma_f32 v49, v34, v210, -v170
	v_fmamk_f32 v49, v171, 0x40000000, v49
	v_cndmask_b32_e32 v33, v243, v33, vcc
	v_cmp_ge_i32_e32 vcc, 2, v211
	v_fma_f32 v50, v35, v210, -v170
	v_fmamk_f32 v50, v171, 0x40400000, v50
	v_cndmask_b32_e32 v49, v243, v49, vcc
	v_cmp_ge_i32_e32 vcc, 3, v211
	v_fma_f32 v51, v36, v210, -v170
	v_fmamk_f32 v51, v171, 0x41000000, v51
	v_cndmask_b32_e32 v50, v243, v50, vcc
	v_cmp_ge_i32_e32 vcc, 8, v211
	v_fma_f32 v37, v37, v210, -v170
	v_fmamk_f32 v37, v171, 0x41100000, v37
	v_cndmask_b32_e32 v51, v243, v51, vcc
	v_cmp_ge_i32_e32 vcc, 9, v211
	v_fma_f32 v52, v38, v210, -v170
	v_fmamk_f32 v52, v171, 0x41200000, v52
	v_cndmask_b32_e32 v37, v243, v37, vcc
	v_cmp_ge_i32_e32 vcc, 10, v211
	v_fma_f32 v39, v39, v210, -v170
	v_fmamk_f32 v39, v171, 0x41300000, v39
	v_cndmask_b32_e32 v52, v243, v52, vcc
	v_cmp_ge_i32_e32 vcc, 11, v211
	v_fma_f32 v53, v40, v210, -v170
	v_fmamk_f32 v53, v171, 0x41800000, v53
	v_cndmask_b32_e32 v39, v243, v39, vcc
	v_cmp_ge_i32_e32 vcc, 16, v211
	v_fma_f32 v41, v41, v210, -v170
	v_fmamk_f32 v41, v171, 0x41880000, v41
	v_cndmask_b32_e32 v53, v243, v53, vcc
	v_cmp_ge_i32_e32 vcc, 17, v211
	v_fma_f32 v42, v42, v210, -v170
	v_fmamk_f32 v42, v171, 0x41900000, v42
	v_cndmask_b32_e32 v41, v243, v41, vcc
	v_cmp_ge_i32_e32 vcc, 18, v211
	v_fma_f32 v43, v43, v210, -v170
	v_fmamk_f32 v43, v171, 0x41980000, v43
	v_cndmask_b32_e32 v42, v243, v42, vcc
	v_cmp_ge_i32_e32 vcc, 19, v211
	v_fma_f32 v44, v44, v210, -v170
	v_fmamk_f32 v44, v171, 0x41c00000, v44
	v_cndmask_b32_e32 v43, v243, v43, vcc
	v_cmp_ge_i32_e32 vcc, 24, v211
	v_fma_f32 v45, v45, v210, -v170
	v_fmamk_f32 v45, v171, 0x41c80000, v45
	v_cndmask_b32_e32 v44, v243, v44, vcc
	v_cmp_ge_i32_e32 vcc, 25, v211
	v_fma_f32 v54, v46, v210, -v170
	v_fmamk_f32 v54, v171, 0x41d00000, v54
	v_cndmask_b32_e32 v45, v243, v45, vcc
	v_cmp_ge_i32_e32 vcc, 26, v211
	v_fma_f32 v55, v47, v210, -v170
	v_fmamk_f32 v55, v171, 0x41d80000, v55
	v_cndmask_b32_e32 v54, v243, v54, vcc
	v_cmp_ge_i32_e32 vcc, 27, v211
	s_nop 1
	v_cndmask_b32_e32 v55, v243, v55, vcc
	s_branch .Ldil_join_4
.Ldil_slow_4:
	v_sub_u32_e32 v49, v167, v48
	v_cvt_f32_i32_e32 v211, v49
	v_lshlrev_b32_e32 v50, s30, v48
	v_cmp_gt_u32_e32 vcc, s6, v49
	v_cmp_lt_i32_e64 s[0:1], s3, v50
	v_or_b32_e32 v49, 1, v48
	s_and_b64 vcc, vcc, s[0:1]
	v_mov_b32_e32 v170, v32
	v_pk_mul_f32 v[50:51], v[170:171], v[210:211]
	v_mov_b32_e32 v170, v33
	v_sub_f32_e32 v32, v50, v51
	v_sub_u32_e32 v50, v167, v49
	v_cvt_f32_i32_e32 v211, v50
	v_lshlrev_b32_e32 v49, s30, v49
	v_cndmask_b32_e32 v32, v243, v32, vcc
	v_cmp_gt_u32_e32 vcc, s6, v50
	v_cmp_lt_i32_e64 s[0:1], s3, v49
	v_pk_mul_f32 v[50:51], v[170:171], v[210:211]
	v_or_b32_e32 v49, 2, v48
	v_sub_f32_e32 v33, v50, v51
	v_sub_u32_e32 v50, v167, v49
	v_cvt_f32_i32_e32 v211, v50
	s_and_b64 vcc, vcc, s[0:1]
	v_lshlrev_b32_e32 v49, s30, v49
	v_mov_b32_e32 v170, v34
	v_cndmask_b32_e32 v33, v243, v33, vcc
	v_cmp_gt_u32_e32 vcc, s6, v50
	v_cmp_lt_i32_e64 s[0:1], s3, v49
	v_pk_mul_f32 v[50:51], v[170:171], v[210:211]
	s_and_b64 vcc, vcc, s[0:1]
	v_sub_f32_e32 v34, v50, v51
	v_cndmask_b32_e32 v49, v243, v34, vcc
	v_or_b32_e32 v34, 3, v48
	v_sub_u32_e32 v50, v167, v34
	v_cvt_f32_i32_e32 v211, v50
	v_lshlrev_b32_e32 v34, s30, v34
	v_mov_b32_e32 v170, v35
	v_cmp_gt_u32_e32 vcc, s6, v50
	v_cmp_lt_i32_e64 s[0:1], s3, v34
	v_pk_mul_f32 v[34:35], v[170:171], v[210:211]
	s_and_b64 vcc, vcc, s[0:1]
	v_sub_f32_e32 v34, v34, v35
	v_cndmask_b32_e32 v50, v243, v34, vcc
	v_or_b32_e32 v34, 8, v48
	v_sub_u32_e32 v35, v167, v34
	v_cvt_f32_i32_e32 v211, v35
	v_lshlrev_b32_e32 v34, s30, v34
	v_mov_b32_e32 v170, v36
	v_cmp_gt_u32_e32 vcc, s6, v35
	v_cmp_lt_i32_e64 s[0:1], s3, v34
	v_pk_mul_f32 v[34:35], v[170:171], v[210:211]
	s_and_b64 vcc, vcc, s[0:1]
	v_sub_f32_e32 v34, v34, v35
	v_cndmask_b32_e32 v51, v243, v34, vcc
	v_or_b32_e32 v34, 9, v48
	v_sub_u32_e32 v35, v167, v34
	v_cvt_f32_i32_e32 v211, v35
	v_lshlrev_b32_e32 v34, s30, v34
	v_mov_b32_e32 v170, v37
	v_cmp_gt_u32_e32 vcc, s6, v35
	v_cmp_lt_i32_e64 s[0:1], s3, v34
	v_pk_mul_f32 v[34:35], v[170:171], v[210:211]
	s_and_b64 vcc, vcc, s[0:1]
	v_sub_f32_e32 v34, v34, v35
	v_cndmask_b32_e32 v37, v243, v34, vcc
	v_or_b32_e32 v34, 10, v48
	v_sub_u32_e32 v35, v167, v34
	v_cvt_f32_i32_e32 v211, v35
	v_lshlrev_b32_e32 v34, s30, v34
	v_mov_b32_e32 v170, v38
	v_cmp_gt_u32_e32 vcc, s6, v35
	v_cmp_lt_i32_e64 s[0:1], s3, v34
	v_pk_mul_f32 v[34:35], v[170:171], v[210:211]
	s_and_b64 vcc, vcc, s[0:1]
	v_sub_f32_e32 v34, v34, v35
	v_cndmask_b32_e32 v52, v243, v34, vcc
	v_or_b32_e32 v34, 11, v48
	v_sub_u32_e32 v35, v167, v34
	v_cvt_f32_i32_e32 v211, v35
	v_lshlrev_b32_e32 v34, s30, v34
	v_mov_b32_e32 v170, v39
	v_cmp_gt_u32_e32 vcc, s6, v35
	v_cmp_lt_i32_e64 s[0:1], s3, v34
	v_pk_mul_f32 v[34:35], v[170:171], v[210:211]
	s_and_b64 vcc, vcc, s[0:1]
	v_sub_f32_e32 v34, v34, v35
	v_cndmask_b32_e32 v39, v243, v34, vcc
	v_or_b32_e32 v34, 16, v48
	v_sub_u32_e32 v35, v167, v34
	v_cvt_f32_i32_e32 v211, v35
	v_lshlrev_b32_e32 v34, s30, v34
	v_mov_b32_e32 v170, v40
	v_cmp_gt_u32_e32 vcc, s6, v35
	v_cmp_lt_i32_e64 s[0:1], s3, v34
	v_pk_mul_f32 v[34:35], v[170:171], v[210:211]
	s_and_b64 vcc, vcc, s[0:1]
	v_sub_f32_e32 v34, v34, v35
	v_cndmask_b32_e32 v53, v243, v34, vcc
	v_or_b32_e32 v34, 17, v48
	v_sub_u32_e32 v35, v167, v34
	v_cvt_f32_i32_e32 v211, v35
	v_lshlrev_b32_e32 v34, s30, v34
	v_mov_b32_e32 v170, v41
	v_cmp_gt_u32_e32 vcc, s6, v35
	v_cmp_lt_i32_e64 s[0:1], s3, v34
	v_pk_mul_f32 v[34:35], v[170:171], v[210:211]
	s_and_b64 vcc, vcc, s[0:1]
	v_sub_f32_e32 v34, v34, v35
	v_cndmask_b32_e32 v41, v243, v34, vcc
	v_or_b32_e32 v34, 18, v48
	v_sub_u32_e32 v35, v167, v34
	v_cvt_f32_i32_e32 v211, v35
	v_lshlrev_b32_e32 v34, s30, v34
	v_mov_b32_e32 v170, v42
	v_cmp_gt_u32_e32 vcc, s6, v35
	v_cmp_lt_i32_e64 s[0:1], s3, v34
	v_pk_mul_f32 v[34:35], v[170:171], v[210:211]
	s_and_b64 vcc, vcc, s[0:1]
	v_sub_f32_e32 v34, v34, v35
	v_cndmask_b32_e32 v42, v243, v34, vcc
	v_or_b32_e32 v34, 19, v48
	v_sub_u32_e32 v35, v167, v34
	v_cvt_f32_i32_e32 v211, v35
	v_lshlrev_b32_e32 v34, s30, v34
	v_mov_b32_e32 v170, v43
	v_cmp_gt_u32_e32 vcc, s6, v35
	v_cmp_lt_i32_e64 s[0:1], s3, v34
	v_pk_mul_f32 v[34:35], v[170:171], v[210:211]
	s_and_b64 vcc, vcc, s[0:1]
	v_sub_f32_e32 v34, v34, v35
	v_cndmask_b32_e32 v43, v243, v34, vcc
	v_or_b32_e32 v34, 24, v48
	v_sub_u32_e32 v35, v167, v34
	v_cvt_f32_i32_e32 v211, v35
	v_lshlrev_b32_e32 v34, s30, v34
	v_mov_b32_e32 v170, v44
	v_cmp_gt_u32_e32 vcc, s6, v35
	v_cmp_lt_i32_e64 s[0:1], s3, v34
	v_pk_mul_f32 v[34:35], v[170:171], v[210:211]
	s_and_b64 vcc, vcc, s[0:1]
	v_sub_f32_e32 v34, v34, v35
	v_cndmask_b32_e32 v44, v243, v34, vcc
	v_or_b32_e32 v34, 25, v48
	v_sub_u32_e32 v35, v167, v34
	v_cvt_f32_i32_e32 v211, v35
	v_lshlrev_b32_e32 v34, s30, v34
	v_mov_b32_e32 v170, v45
	v_cmp_gt_u32_e32 vcc, s6, v35
	v_cmp_lt_i32_e64 s[0:1], s3, v34
	v_pk_mul_f32 v[34:35], v[170:171], v[210:211]
	s_and_b64 vcc, vcc, s[0:1]
	v_sub_f32_e32 v34, v34, v35
	v_cndmask_b32_e32 v45, v243, v34, vcc
	v_or_b32_e32 v34, 26, v48
	v_sub_u32_e32 v35, v167, v34
	v_cvt_f32_i32_e32 v211, v35
	v_lshlrev_b32_e32 v34, s30, v34
	v_mov_b32_e32 v170, v46
	v_cmp_gt_u32_e32 vcc, s6, v35
	v_cmp_lt_i32_e64 s[0:1], s3, v34
	v_pk_mul_f32 v[34:35], v[170:171], v[210:211]
	s_and_b64 vcc, vcc, s[0:1]
	v_sub_f32_e32 v34, v34, v35
	v_cndmask_b32_e32 v54, v243, v34, vcc
	v_or_b32_e32 v34, 27, v48
	v_sub_u32_e32 v35, v167, v34
	v_cvt_f32_i32_e32 v211, v35
	v_lshlrev_b32_e32 v34, s30, v34
	v_mov_b32_e32 v170, v47
	v_cmp_gt_u32_e32 vcc, s6, v35
	v_cmp_lt_i32_e64 s[0:1], s3, v34
	v_pk_mul_f32 v[34:35], v[170:171], v[210:211]
	s_and_b64 vcc, vcc, s[0:1]
	v_sub_f32_e32 v34, v34, v35
	v_cndmask_b32_e32 v55, v243, v34, vcc
.Ldil_join_4:
	v_max_f32_e32 v40, v54, v55
	v_max_f32_e32 v34, v49, v50
	v_max_f32_e32 v35, v52, v39
	v_max_f32_e32 v36, v53, v41
	v_max_f32_e32 v38, v42, v43
	v_max3_f32 v40, v44, v45, v40
	v_max3_f32 v34, v32, v33, v34
	v_max3_f32 v35, v51, v37, v35
	v_max3_f32 v36, v36, v38, v40
	v_max3_f32 v34, v34, v35, v36
	v_mov_b32_e32 v35, v34
	s_nop 1
	v_permlane32_swap_b32_e32 v34, v35
	v_max3_f32 v56, v66, v34, v35
	v_sub_f32_e32 v33, v33, v56
	v_exp_f32_e32 v34, v33
	v_sub_f32_e32 v33, v49, v56
	v_exp_f32_e32 v36, v33
	v_sub_f32_e32 v33, v50, v56
	v_exp_f32_e32 v38, v33
	v_sub_f32_e32 v33, v51, v56
	v_exp_f32_e32 v40, v33
	v_sub_f32_e32 v33, v37, v56
	v_exp_f32_e32 v46, v33
	v_sub_f32_e32 v33, v52, v56
	v_exp_f32_e32 v48, v33
	v_sub_f32_e32 v33, v39, v56
	v_sub_f32_e32 v37, v42, v56
	v_sub_f32_e32 v42, v45, v56
	v_sub_f32_e32 v32, v32, v56
	v_exp_f32_e32 v50, v33
	v_sub_f32_e32 v33, v53, v56
	v_sub_f32_e32 v35, v41, v56
	v_sub_f32_e32 v39, v43, v56
	v_exp_f32_e32 v47, v42
	v_sub_f32_e32 v42, v54, v56
	v_exp_f32_e32 v32, v32
	v_exp_f32_e32 v33, v33
	v_exp_f32_e32 v35, v35
	v_exp_f32_e32 v37, v37
	v_exp_f32_e32 v39, v39
	v_sub_f32_e32 v41, v44, v56
	v_exp_f32_e32 v49, v42
	v_sub_f32_e32 v42, v55, v56
	v_exp_f32_e32 v41, v41
	v_exp_f32_e32 v51, v42
	v_sub_f32_e32 v57, v66, v56
	v_pk_add_f32 v[44:45], v[32:33], v[34:35]
	v_pk_add_f32 v[52:53], v[36:37], v[38:39]
	v_exp_f32_e32 v42, v57
	v_pk_add_f32 v[44:45], v[44:45], v[52:53]
	v_pk_add_f32 v[52:53], v[40:41], v[46:47]
	v_pk_add_f32 v[54:55], v[48:49], v[50:51]
	v_pk_mul_f32 v[30:31], v[30:31], v[42:43] op_sel_hi:[1,0]
	v_pk_add_f32 v[52:53], v[52:53], v[54:55]
	v_pk_mul_f32 v[28:29], v[28:29], v[42:43] op_sel_hi:[1,0]
	v_pk_add_f32 v[44:45], v[44:45], v[52:53]
	v_pk_mul_f32 v[26:27], v[26:27], v[42:43] op_sel_hi:[1,0]
	v_add_f32_e32 v52, v44, v45
	v_pk_mul_f32 v[24:25], v[24:25], v[42:43] op_sel_hi:[1,0]
	v_pk_mul_f32 v[22:23], v[22:23], v[42:43] op_sel_hi:[1,0]
	v_pk_mul_f32 v[20:21], v[20:21], v[42:43] op_sel_hi:[1,0]
	v_pk_mul_f32 v[18:19], v[18:19], v[42:43] op_sel_hi:[1,0]
	v_pk_mul_f32 v[16:17], v[16:17], v[42:43] op_sel_hi:[1,0]
	v_pk_mul_f32 v[14:15], v[14:15], v[42:43] op_sel_hi:[1,0]
	v_pk_mul_f32 v[12:13], v[12:13], v[42:43] op_sel_hi:[1,0]
	v_pk_mul_f32 v[10:11], v[10:11], v[42:43] op_sel_hi:[1,0]
	v_pk_mul_f32 v[8:9], v[8:9], v[42:43] op_sel_hi:[1,0]
	v_pk_mul_f32 v[6:7], v[6:7], v[42:43] op_sel_hi:[1,0]
	v_pk_mul_f32 v[4:5], v[4:5], v[42:43] op_sel_hi:[1,0]
	v_pk_mul_f32 v[2:3], v[2:3], v[42:43] op_sel_hi:[1,0]
	v_pk_mul_f32 v[0:1], v[0:1], v[42:43] op_sel_hi:[1,0]
	v_fmac_f32_e32 v52, v64, v42
	v_cvt_pk_bf16_f32 v42, v32, v34
	v_cvt_pk_bf16_f32 v43, v36, v38
	v_cvt_pk_bf16_f32 v44, v40, v46
	v_cvt_pk_bf16_f32 v45, v48, v50
	v_cvt_pk_bf16_f32 v32, v33, v35
	v_cvt_pk_bf16_f32 v33, v37, v39
	v_cvt_pk_bf16_f32 v34, v41, v47
	v_cvt_pk_bf16_f32 v35, v49, v51
	s_waitcnt lgkmcnt(0)
	ds_read_b64_tr_b16 v[36:37], v179
	ds_read_b64_tr_b16 v[38:39], v179 offset:512
	s_waitcnt lgkmcnt(0)
	v_mfma_f32_32x32x16_bf16 v[16:31], v[36:39], v[42:45], v[16:31]
	ds_read_b64_tr_b16 v[36:37], v179 offset:1024
	ds_read_b64_tr_b16 v[38:39], v179 offset:1536
	v_mov_b32_e32 v66, v56
	v_mov_b32_e32 v64, v52
	s_waitcnt lgkmcnt(0)
	v_mfma_f32_32x32x16_bf16 v[16:31], v[36:39], v[32:35], v[16:31]
	ds_read_b64_tr_b16 v[36:37], v179 offset:2048
	ds_read_b64_tr_b16 v[38:39], v179 offset:2560
	s_waitcnt lgkmcnt(0)
	v_mfma_f32_32x32x16_bf16 v[0:15], v[36:39], v[42:45], v[0:15]
	ds_read_b64_tr_b16 v[36:37], v179 offset:3072
	ds_read_b64_tr_b16 v[38:39], v179 offset:3584
	s_waitcnt lgkmcnt(0)
	v_mfma_f32_32x32x16_bf16 v[0:15], v[36:39], v[32:35], v[0:15]
